# nt hint on the SwiGLU epilogue's ACT stores (keep xb and weights cache-resident during FFN-in)
# baseline (speedup 1.0000x reference)
.LBB0_172:
	v_lshl_add_u32 v153, s69, 8, v3
	v_and_b32_e32 v145, 0x7cf, v153
	v_lshl_add_u32 v147, v145, 2, s92
	v_bitop3_b32 v145, v153, s5, 16 bitop3:0xc8
	v_lshl_add_u32 v149, v145, 2, s92
	v_bitop3_b32 v145, v153, s8, 32 bitop3:0xc8
	v_lshl_add_u32 v150, v145, 2, s92
	v_bitop3_b32 v145, v153, s9, 48 bitop3:0xc8
	v_add_u32_e32 v176, 0x80, v153
	v_lshl_add_u32 v151, v145, 2, s92
	v_and_b32_e32 v145, 0x7cf, v176
	v_add_u32_e32 v148, 0x90, v153
	v_lshl_add_u32 v152, v145, 2, s92
	v_and_b32_e32 v145, 0x7df, v148
	v_add_u32_e32 v146, 0xa0, v153
	v_lshl_add_u32 v154, v145, 2, s92
	v_and_b32_e32 v145, 0x7ef, v146
	v_lshl_add_u32 v172, v145, 2, s92
	v_add_u32_e32 v145, 0xb0, v153
	v_and_b32_e32 v173, 0x7ff, v145
	v_lshl_add_u32 v173, v173, 2, s92
	ds_read_b32 v177, v147
	ds_read_b32 v178, v149
	ds_read_b32 v179, v150
	ds_read_b32 v180, v151
	ds_read_b32 v181, v152
	ds_read_b32 v182, v154
	ds_read_b32 v149, v172
	ds_read_b32 v147, v173
	s_waitcnt lgkmcnt(0)
	v_mul_f32_e32 v152, 0xbfb8aa3b, v177
	v_pk_mul_f32 v[172:173], v[128:129], v[152:153] op_sel_hi:[1,0]
	v_pk_mul_f32 v[122:123], v[130:131], v[122:123]
	v_pk_mul_f32 v[120:121], v[128:129], v[120:121]
	v_exp_f32_e32 v128, v172
	v_exp_f32_e32 v129, v173
	v_pk_mul_f32 v[130:131], v[130:131], v[152:153] op_sel_hi:[1,0]
	v_pk_mul_f32 v[172:173], v[124:125], v[152:153] op_sel_hi:[1,0]
	v_exp_f32_e32 v130, v130
	v_exp_f32_e32 v131, v131
	v_pk_mul_f32 v[118:119], v[126:127], v[118:119]
	v_pk_mul_f32 v[116:117], v[124:125], v[116:117]
	v_exp_f32_e32 v124, v172
	v_exp_f32_e32 v125, v173
	v_pk_mul_f32 v[126:127], v[126:127], v[152:153] op_sel_hi:[1,0]
	v_pk_add_f32 v[128:129], v[128:129], 1.0 op_sel_hi:[1,0]
	v_exp_f32_e32 v126, v126
	v_exp_f32_e32 v127, v127
	v_pk_add_f32 v[130:131], v[130:131], 1.0 op_sel_hi:[1,0]
	v_pk_add_f32 v[124:125], v[124:125], 1.0 op_sel_hi:[1,0]
	v_rcp_f32_e32 v128, v128
	v_rcp_f32_e32 v129, v129
	v_rcp_f32_e32 v130, v130
	v_rcp_f32_e32 v131, v131
	v_rcp_f32_e32 v124, v124
	v_rcp_f32_e32 v125, v125
	v_pk_add_f32 v[126:127], v[126:127], 1.0 op_sel_hi:[1,0]
	v_or_b32_e32 v155, 16, v153
	v_rcp_f32_e32 v126, v126
	v_rcp_f32_e32 v127, v127
	v_mul_f32_e32 v154, v177, v177
	v_pk_mul_f32 v[120:121], v[120:121], v[154:155] op_sel_hi:[1,0]
	v_pk_mul_f32 v[122:123], v[122:123], v[154:155] op_sel_hi:[1,0]
	v_pk_mul_f32 v[116:117], v[116:117], v[154:155] op_sel_hi:[1,0]
	v_lshl_or_b32 v150, s64, 7, v143
	v_pk_mul_f32 v[118:119], v[118:119], v[154:155] op_sel_hi:[1,0]
	v_pk_mul_f32 v[120:121], v[120:121], v[128:129]
	v_pk_mul_f32 v[122:123], v[122:123], v[130:131]
	v_pk_mul_f32 v[116:117], v[116:117], v[124:125]
	v_ashrrev_i32_e32 v151, 31, v150
	v_pk_mul_f32 v[118:119], v[118:119], v[126:127]
	v_cvt_pk_bf16_f32 v120, v120, v121
	v_cvt_pk_bf16_f32 v121, v122, v123
	v_cvt_pk_bf16_f32 v122, v116, v117
	v_mov_b64_e32 v[116:117], s[22:23]
	v_cvt_pk_bf16_f32 v123, v118, v119
	v_mad_i64_i32 v[124:125], s[34:35], v153, s11, v[116:117]
	v_lshlrev_b64 v[118:119], 1, v[150:151]
	v_lshl_add_u64 v[124:125], v[124:125], 0, v[118:119]
	global_store_dwordx4 v[124:125], v[120:123], off nt
	v_pk_mul_f32 v[104:105], v[112:113], v[104:105]
	v_pk_mul_f32 v[100:101], v[108:109], v[100:101]
	v_mul_f32_e32 v120, 0xbfb8aa3b, v178
	v_pk_mul_f32 v[124:125], v[112:113], v[120:121] op_sel_hi:[1,0]
	v_pk_mul_f32 v[106:107], v[114:115], v[106:107]
	v_exp_f32_e32 v112, v124
	v_exp_f32_e32 v113, v125
	v_pk_mul_f32 v[124:125], v[108:109], v[120:121] op_sel_hi:[1,0]
	v_pk_mul_f32 v[114:115], v[114:115], v[120:121] op_sel_hi:[1,0]
	v_exp_f32_e32 v108, v124
	v_exp_f32_e32 v109, v125
	v_pk_mul_f32 v[102:103], v[110:111], v[102:103]
	v_pk_mul_f32 v[110:111], v[110:111], v[120:121] op_sel_hi:[1,0]
	v_exp_f32_e32 v114, v114
	v_exp_f32_e32 v115, v115
	v_exp_f32_e32 v110, v110
	v_exp_f32_e32 v111, v111
	v_pk_add_f32 v[112:113], v[112:113], 1.0 op_sel_hi:[1,0]
	v_pk_add_f32 v[108:109], v[108:109], 1.0 op_sel_hi:[1,0]
	v_rcp_f32_e32 v112, v112
	v_rcp_f32_e32 v113, v113
	v_rcp_f32_e32 v108, v108
	v_rcp_f32_e32 v109, v109
	v_mul_f32_e32 v122, v178, v178
	v_pk_add_f32 v[114:115], v[114:115], 1.0 op_sel_hi:[1,0]
	v_pk_add_f32 v[110:111], v[110:111], 1.0 op_sel_hi:[1,0]
	v_pk_mul_f32 v[104:105], v[104:105], v[122:123] op_sel_hi:[1,0]
	v_rcp_f32_e32 v114, v114
	v_rcp_f32_e32 v115, v115
	v_rcp_f32_e32 v110, v110
	v_rcp_f32_e32 v111, v111
	v_pk_mul_f32 v[100:101], v[100:101], v[122:123] op_sel_hi:[1,0]
	v_pk_mul_f32 v[104:105], v[104:105], v[112:113]
	v_pk_mul_f32 v[108:109], v[100:101], v[108:109]
	v_cvt_pk_bf16_f32 v100, v104, v105
	v_mad_i64_i32 v[104:105], s[34:35], v155, s11, v[116:117]
	v_pk_mul_f32 v[106:107], v[106:107], v[122:123] op_sel_hi:[1,0]
	v_pk_mul_f32 v[102:103], v[102:103], v[122:123] op_sel_hi:[1,0]
	v_lshl_add_u64 v[104:105], v[104:105], 0, v[118:119]
	v_pk_mul_f32 v[106:107], v[106:107], v[114:115]
	v_pk_mul_f32 v[110:111], v[102:103], v[110:111]
	v_cvt_pk_bf16_f32 v101, v106, v107
	v_cvt_pk_bf16_f32 v102, v108, v109
	v_pk_mul_f32 v[88:89], v[96:97], v[88:89]
	v_cvt_pk_bf16_f32 v103, v110, v111
	global_store_dwordx4 v[104:105], v[100:103], off nt
	v_pk_mul_f32 v[84:85], v[92:93], v[84:85]
	v_pk_mul_f32 v[90:91], v[98:99], v[90:91]
	v_mul_f32_e32 v100, 0xbfb8aa3b, v179
	v_pk_mul_f32 v[104:105], v[96:97], v[100:101] op_sel_hi:[1,0]
	v_pk_mul_f32 v[98:99], v[98:99], v[100:101] op_sel_hi:[1,0]
	v_exp_f32_e32 v96, v104
	v_exp_f32_e32 v97, v105
	v_pk_mul_f32 v[104:105], v[92:93], v[100:101] op_sel_hi:[1,0]
	v_pk_mul_f32 v[86:87], v[94:95], v[86:87]
	v_exp_f32_e32 v92, v104
	v_exp_f32_e32 v93, v105
	v_pk_mul_f32 v[94:95], v[94:95], v[100:101] op_sel_hi:[1,0]
	v_exp_f32_e32 v98, v98
	v_exp_f32_e32 v99, v99
	v_exp_f32_e32 v94, v94
	v_exp_f32_e32 v95, v95
	v_pk_add_f32 v[96:97], v[96:97], 1.0 op_sel_hi:[1,0]
	v_pk_add_f32 v[92:93], v[92:93], 1.0 op_sel_hi:[1,0]
	v_rcp_f32_e32 v96, v96
	v_rcp_f32_e32 v97, v97
	v_rcp_f32_e32 v92, v92
	v_rcp_f32_e32 v93, v93
	v_mul_f32_e32 v102, v179, v179
	v_pk_add_f32 v[98:99], v[98:99], 1.0 op_sel_hi:[1,0]
	v_pk_add_f32 v[94:95], v[94:95], 1.0 op_sel_hi:[1,0]
	v_pk_mul_f32 v[88:89], v[88:89], v[102:103] op_sel_hi:[1,0]
	v_rcp_f32_e32 v98, v98
	v_rcp_f32_e32 v99, v99
	v_rcp_f32_e32 v94, v94
	v_rcp_f32_e32 v95, v95
	v_or_b32_e32 v174, 32, v153
	v_pk_mul_f32 v[84:85], v[84:85], v[102:103] op_sel_hi:[1,0]
	v_pk_mul_f32 v[88:89], v[88:89], v[96:97]
	v_pk_mul_f32 v[92:93], v[84:85], v[92:93]
	v_cvt_pk_bf16_f32 v84, v88, v89
	v_mad_i64_i32 v[88:89], s[34:35], v174, s11, v[116:117]
	v_pk_mul_f32 v[90:91], v[90:91], v[102:103] op_sel_hi:[1,0]
	v_pk_mul_f32 v[86:87], v[86:87], v[102:103] op_sel_hi:[1,0]
	v_lshl_add_u64 v[88:89], v[88:89], 0, v[118:119]
	v_pk_mul_f32 v[90:91], v[90:91], v[98:99]
	v_pk_mul_f32 v[94:95], v[86:87], v[94:95]
	v_cvt_pk_bf16_f32 v85, v90, v91
	v_cvt_pk_bf16_f32 v86, v92, v93
	v_pk_mul_f32 v[72:73], v[80:81], v[72:73]
	v_cvt_pk_bf16_f32 v87, v94, v95
	global_store_dwordx4 v[88:89], v[84:87], off nt
	v_pk_mul_f32 v[68:69], v[76:77], v[68:69]
	v_pk_mul_f32 v[74:75], v[82:83], v[74:75]
	v_mul_f32_e32 v84, 0xbfb8aa3b, v180
	v_pk_mul_f32 v[88:89], v[80:81], v[84:85] op_sel_hi:[1,0]
	v_pk_mul_f32 v[82:83], v[82:83], v[84:85] op_sel_hi:[1,0]
	v_exp_f32_e32 v80, v88
	v_exp_f32_e32 v81, v89
	v_pk_mul_f32 v[88:89], v[76:77], v[84:85] op_sel_hi:[1,0]
	v_pk_mul_f32 v[70:71], v[78:79], v[70:71]
	v_exp_f32_e32 v76, v88
	v_exp_f32_e32 v77, v89
	v_pk_mul_f32 v[78:79], v[78:79], v[84:85] op_sel_hi:[1,0]
	v_exp_f32_e32 v82, v82
	v_exp_f32_e32 v83, v83
	v_exp_f32_e32 v78, v78
	v_exp_f32_e32 v79, v79
	v_pk_add_f32 v[80:81], v[80:81], 1.0 op_sel_hi:[1,0]
	v_pk_add_f32 v[76:77], v[76:77], 1.0 op_sel_hi:[1,0]
	v_rcp_f32_e32 v80, v80
	v_rcp_f32_e32 v81, v81
	v_rcp_f32_e32 v76, v76
	v_rcp_f32_e32 v77, v77
	v_mul_f32_e32 v86, v180, v180
	v_pk_add_f32 v[82:83], v[82:83], 1.0 op_sel_hi:[1,0]
	v_pk_add_f32 v[78:79], v[78:79], 1.0 op_sel_hi:[1,0]
	v_pk_mul_f32 v[72:73], v[72:73], v[86:87] op_sel_hi:[1,0]
	v_rcp_f32_e32 v82, v82
	v_rcp_f32_e32 v83, v83
	v_rcp_f32_e32 v78, v78
	v_rcp_f32_e32 v79, v79
	v_or_b32_e32 v175, 48, v153
	v_pk_mul_f32 v[68:69], v[68:69], v[86:87] op_sel_hi:[1,0]
	v_pk_mul_f32 v[72:73], v[72:73], v[80:81]
	v_pk_mul_f32 v[76:77], v[68:69], v[76:77]
	v_cvt_pk_bf16_f32 v68, v72, v73
	v_mad_i64_i32 v[72:73], s[34:35], v175, s11, v[116:117]
	v_pk_mul_f32 v[74:75], v[74:75], v[86:87] op_sel_hi:[1,0]
	v_pk_mul_f32 v[70:71], v[70:71], v[86:87] op_sel_hi:[1,0]
	v_lshl_add_u64 v[72:73], v[72:73], 0, v[118:119]
	v_pk_mul_f32 v[74:75], v[74:75], v[82:83]
	v_pk_mul_f32 v[78:79], v[70:71], v[78:79]
	v_cvt_pk_bf16_f32 v69, v74, v75
	v_cvt_pk_bf16_f32 v70, v76, v77
	v_pk_mul_f32 v[56:57], v[64:65], v[56:57]
	v_cvt_pk_bf16_f32 v71, v78, v79
	global_store_dwordx4 v[72:73], v[68:71], off nt
	v_pk_mul_f32 v[52:53], v[60:61], v[52:53]
	v_pk_mul_f32 v[58:59], v[66:67], v[58:59]
	v_mul_f32_e32 v68, 0xbfb8aa3b, v181
	v_pk_mul_f32 v[72:73], v[64:65], v[68:69] op_sel_hi:[1,0]
	v_pk_mul_f32 v[66:67], v[66:67], v[68:69] op_sel_hi:[1,0]
	v_exp_f32_e32 v64, v72
	v_exp_f32_e32 v65, v73
	v_pk_mul_f32 v[72:73], v[60:61], v[68:69] op_sel_hi:[1,0]
	v_pk_mul_f32 v[54:55], v[62:63], v[54:55]
	v_exp_f32_e32 v60, v72
	v_exp_f32_e32 v61, v73
	v_pk_mul_f32 v[62:63], v[62:63], v[68:69] op_sel_hi:[1,0]
	v_exp_f32_e32 v66, v66
	v_exp_f32_e32 v67, v67
	v_exp_f32_e32 v62, v62
	v_exp_f32_e32 v63, v63
	v_pk_add_f32 v[64:65], v[64:65], 1.0 op_sel_hi:[1,0]
	v_pk_add_f32 v[60:61], v[60:61], 1.0 op_sel_hi:[1,0]
	v_rcp_f32_e32 v64, v64
	v_rcp_f32_e32 v65, v65
	v_rcp_f32_e32 v60, v60
	v_rcp_f32_e32 v61, v61
	v_mul_f32_e32 v70, v181, v181
	v_pk_add_f32 v[66:67], v[66:67], 1.0 op_sel_hi:[1,0]
	v_pk_add_f32 v[62:63], v[62:63], 1.0 op_sel_hi:[1,0]
	v_pk_mul_f32 v[56:57], v[56:57], v[70:71] op_sel_hi:[1,0]
	v_rcp_f32_e32 v66, v66
	v_rcp_f32_e32 v67, v67
	v_rcp_f32_e32 v62, v62
	v_rcp_f32_e32 v63, v63
	v_pk_mul_f32 v[52:53], v[52:53], v[70:71] op_sel_hi:[1,0]
	v_pk_mul_f32 v[56:57], v[56:57], v[64:65]
	v_pk_mul_f32 v[60:61], v[52:53], v[60:61]
	v_cvt_pk_bf16_f32 v52, v56, v57
	v_mad_i64_i32 v[56:57], s[34:35], v176, s11, v[116:117]
	v_pk_mul_f32 v[58:59], v[58:59], v[70:71] op_sel_hi:[1,0]
	v_pk_mul_f32 v[54:55], v[54:55], v[70:71] op_sel_hi:[1,0]
	v_lshl_add_u64 v[56:57], v[56:57], 0, v[118:119]
	v_pk_mul_f32 v[58:59], v[58:59], v[66:67]
	v_pk_mul_f32 v[62:63], v[54:55], v[62:63]
	v_cvt_pk_bf16_f32 v53, v58, v59
	v_cvt_pk_bf16_f32 v54, v60, v61
	v_pk_mul_f32 v[40:41], v[48:49], v[40:41]
	v_cvt_pk_bf16_f32 v55, v62, v63
	global_store_dwordx4 v[56:57], v[52:55], off nt
	v_pk_mul_f32 v[36:37], v[44:45], v[36:37]
	v_pk_mul_f32 v[42:43], v[50:51], v[42:43]
	v_mul_f32_e32 v52, 0xbfb8aa3b, v182
	v_pk_mul_f32 v[56:57], v[48:49], v[52:53] op_sel_hi:[1,0]
	v_pk_mul_f32 v[50:51], v[50:51], v[52:53] op_sel_hi:[1,0]
	v_exp_f32_e32 v48, v56
	v_exp_f32_e32 v49, v57
	v_pk_mul_f32 v[56:57], v[44:45], v[52:53] op_sel_hi:[1,0]
	v_pk_mul_f32 v[38:39], v[46:47], v[38:39]
	v_exp_f32_e32 v44, v56
	v_exp_f32_e32 v45, v57
	v_pk_mul_f32 v[46:47], v[46:47], v[52:53] op_sel_hi:[1,0]
	v_exp_f32_e32 v50, v50
	v_exp_f32_e32 v51, v51
	v_exp_f32_e32 v46, v46
	v_exp_f32_e32 v47, v47
	v_pk_add_f32 v[48:49], v[48:49], 1.0 op_sel_hi:[1,0]
	v_pk_add_f32 v[44:45], v[44:45], 1.0 op_sel_hi:[1,0]
	v_rcp_f32_e32 v48, v48
	v_rcp_f32_e32 v49, v49
	v_rcp_f32_e32 v44, v44
	v_rcp_f32_e32 v45, v45
	v_mul_f32_e32 v54, v182, v182
	v_pk_add_f32 v[50:51], v[50:51], 1.0 op_sel_hi:[1,0]
	v_pk_add_f32 v[46:47], v[46:47], 1.0 op_sel_hi:[1,0]
	v_pk_mul_f32 v[40:41], v[40:41], v[54:55] op_sel_hi:[1,0]
	v_rcp_f32_e32 v50, v50
	v_rcp_f32_e32 v51, v51
	v_rcp_f32_e32 v46, v46
	v_rcp_f32_e32 v47, v47
	v_pk_mul_f32 v[36:37], v[36:37], v[54:55] op_sel_hi:[1,0]
	v_pk_mul_f32 v[40:41], v[40:41], v[48:49]
	v_pk_mul_f32 v[44:45], v[36:37], v[44:45]
	v_cvt_pk_bf16_f32 v36, v40, v41
	v_mad_i64_i32 v[40:41], s[34:35], v148, s11, v[116:117]
	v_pk_mul_f32 v[42:43], v[42:43], v[54:55] op_sel_hi:[1,0]
	v_pk_mul_f32 v[38:39], v[38:39], v[54:55] op_sel_hi:[1,0]
	v_lshl_add_u64 v[40:41], v[40:41], 0, v[118:119]
	v_pk_mul_f32 v[42:43], v[42:43], v[50:51]
	v_pk_mul_f32 v[46:47], v[38:39], v[46:47]
	v_cvt_pk_bf16_f32 v37, v42, v43
	v_cvt_pk_bf16_f32 v38, v44, v45
	v_pk_mul_f32 v[24:25], v[32:33], v[24:25]
	v_cvt_pk_bf16_f32 v39, v46, v47
	global_store_dwordx4 v[40:41], v[36:39], off nt
	v_pk_mul_f32 v[20:21], v[28:29], v[20:21]
	v_pk_mul_f32 v[26:27], v[34:35], v[26:27]
	v_mul_f32_e32 v36, 0xbfb8aa3b, v149
	v_pk_mul_f32 v[40:41], v[32:33], v[36:37] op_sel_hi:[1,0]
	v_pk_mul_f32 v[34:35], v[34:35], v[36:37] op_sel_hi:[1,0]
	v_exp_f32_e32 v32, v40
	v_exp_f32_e32 v33, v41
	v_pk_mul_f32 v[40:41], v[28:29], v[36:37] op_sel_hi:[1,0]
	v_pk_mul_f32 v[22:23], v[30:31], v[22:23]
	v_exp_f32_e32 v28, v40
	v_exp_f32_e32 v29, v41
	v_pk_mul_f32 v[30:31], v[30:31], v[36:37] op_sel_hi:[1,0]
	v_exp_f32_e32 v34, v34
	v_exp_f32_e32 v35, v35
	v_exp_f32_e32 v30, v30
	v_exp_f32_e32 v31, v31
	v_pk_add_f32 v[32:33], v[32:33], 1.0 op_sel_hi:[1,0]
	v_pk_add_f32 v[28:29], v[28:29], 1.0 op_sel_hi:[1,0]
	v_rcp_f32_e32 v32, v32
	v_rcp_f32_e32 v33, v33
	v_rcp_f32_e32 v28, v28
	v_rcp_f32_e32 v29, v29
	v_mul_f32_e32 v38, v149, v149
	v_pk_add_f32 v[34:35], v[34:35], 1.0 op_sel_hi:[1,0]
	v_pk_add_f32 v[30:31], v[30:31], 1.0 op_sel_hi:[1,0]
	v_pk_mul_f32 v[24:25], v[24:25], v[38:39] op_sel_hi:[1,0]
	v_rcp_f32_e32 v34, v34
	v_rcp_f32_e32 v35, v35
	v_rcp_f32_e32 v30, v30
	v_rcp_f32_e32 v31, v31
	v_pk_mul_f32 v[20:21], v[20:21], v[38:39] op_sel_hi:[1,0]
	v_pk_mul_f32 v[24:25], v[24:25], v[32:33]
	v_pk_mul_f32 v[28:29], v[20:21], v[28:29]
	v_cvt_pk_bf16_f32 v20, v24, v25
	v_mad_i64_i32 v[24:25], s[34:35], v146, s11, v[116:117]
	v_pk_mul_f32 v[26:27], v[26:27], v[38:39] op_sel_hi:[1,0]
	v_pk_mul_f32 v[22:23], v[22:23], v[38:39] op_sel_hi:[1,0]
	v_lshl_add_u64 v[24:25], v[24:25], 0, v[118:119]
	v_pk_mul_f32 v[26:27], v[26:27], v[34:35]
	v_pk_mul_f32 v[30:31], v[22:23], v[30:31]
	v_cvt_pk_bf16_f32 v21, v26, v27
	v_cvt_pk_bf16_f32 v22, v28, v29
	v_pk_mul_f32 v[8:9], v[16:17], v[8:9]
	v_cvt_pk_bf16_f32 v23, v30, v31
	global_store_dwordx4 v[24:25], v[20:23], off nt
	v_pk_mul_f32 v[4:5], v[12:13], v[4:5]
	v_pk_mul_f32 v[10:11], v[18:19], v[10:11]
	v_mul_f32_e32 v20, 0xbfb8aa3b, v147
	v_pk_mul_f32 v[24:25], v[16:17], v[20:21] op_sel_hi:[1,0]
	v_pk_mul_f32 v[18:19], v[18:19], v[20:21] op_sel_hi:[1,0]
	v_exp_f32_e32 v16, v24
	v_exp_f32_e32 v17, v25
	v_pk_mul_f32 v[24:25], v[12:13], v[20:21] op_sel_hi:[1,0]
	v_pk_mul_f32 v[6:7], v[14:15], v[6:7]
	v_exp_f32_e32 v12, v24
	v_exp_f32_e32 v13, v25
	v_pk_mul_f32 v[14:15], v[14:15], v[20:21] op_sel_hi:[1,0]
	v_exp_f32_e32 v18, v18
	v_exp_f32_e32 v19, v19
	v_exp_f32_e32 v14, v14
	v_exp_f32_e32 v15, v15
	v_pk_add_f32 v[16:17], v[16:17], 1.0 op_sel_hi:[1,0]
	v_pk_add_f32 v[12:13], v[12:13], 1.0 op_sel_hi:[1,0]
	v_rcp_f32_e32 v16, v16
	v_rcp_f32_e32 v17, v17
	v_rcp_f32_e32 v12, v12
	v_rcp_f32_e32 v13, v13
	v_mul_f32_e32 v22, v147, v147
	v_pk_add_f32 v[18:19], v[18:19], 1.0 op_sel_hi:[1,0]
	v_pk_add_f32 v[14:15], v[14:15], 1.0 op_sel_hi:[1,0]
	v_pk_mul_f32 v[8:9], v[8:9], v[22:23] op_sel_hi:[1,0]
	v_rcp_f32_e32 v18, v18
	v_rcp_f32_e32 v19, v19
	v_rcp_f32_e32 v14, v14
	v_rcp_f32_e32 v15, v15
	v_pk_mul_f32 v[4:5], v[4:5], v[22:23] op_sel_hi:[1,0]
	v_pk_mul_f32 v[8:9], v[8:9], v[16:17]
	v_pk_mul_f32 v[12:13], v[4:5], v[12:13]
	v_cvt_pk_bf16_f32 v4, v8, v9
	v_mad_i64_i32 v[8:9], s[34:35], v145, s11, v[116:117]
	v_pk_mul_f32 v[10:11], v[10:11], v[22:23] op_sel_hi:[1,0]
	v_pk_mul_f32 v[6:7], v[6:7], v[22:23] op_sel_hi:[1,0]
	v_lshl_add_u64 v[8:9], v[8:9], 0, v[118:119]
	s_andn2_b64 vcc, exec, s[38:39]
	s_mov_b64 s[34:35], -1
	v_pk_mul_f32 v[10:11], v[10:11], v[18:19]
	v_pk_mul_f32 v[14:15], v[6:7], v[14:15]
	v_cvt_pk_bf16_f32 v5, v10, v11
	v_cvt_pk_bf16_f32 v6, v12, v13
	s_nop 0
	v_cvt_pk_bf16_f32 v7, v14, v15
	global_store_dwordx4 v[8:9], v[4:7], off nt
	s_cbranch_vccnz .LBB0_165
	s_andn2_b64 vcc, exec, s[26:27]
	s_cbranch_vccnz .LBB0_164
	s_barrier
	s_branch .LBB0_164
